# nt (streaming) hint on the one-shot f32 weight loads of all five transpose loops, so they stop evicting reused data from L2/MALL
# speedup vs baseline: 1.0108x; 1.0108x over previous
.LBB0_38:
	s_lshl_b32 s8, s3, 1
	s_lshl_b32 s9, s6, 1
	v_or_b32_e32 v3, s8, v15
	v_or_b32_e32 v7, s9, v14
	s_add_i32 s10, s8, 4
	s_add_i32 s14, s9, 4
	s_add_i32 s15, s8, 8
	s_add_i32 s16, s9, 8
	s_add_i32 s17, s8, 12
	s_add_i32 s18, s9, 12
	s_add_i32 s19, s8, 16
	s_add_i32 s20, s9, 16
	s_add_i32 s21, s8, 20
	s_add_i32 s22, s9, 20
	s_add_i32 s23, s8, 24
	s_add_i32 s24, s9, 24
	s_add_i32 s8, s8, 28
	s_add_i32 s9, s9, 28
	v_add_u32_e32 v25, v7, v6
	v_or_b32_e32 v27, s10, v15
	v_or_b32_e32 v29, s14, v14
	v_or_b32_e32 v63, s15, v15
	v_or_b32_e32 v90, s16, v14
	v_or_b32_e32 v91, s17, v15
	v_or_b32_e32 v92, s18, v14
	v_or_b32_e32 v93, s19, v15
	v_or_b32_e32 v94, s20, v14
	v_or_b32_e32 v95, s21, v15
	v_or_b32_e32 v96, s22, v14
	v_or_b32_e32 v97, s23, v15
	v_or_b32_e32 v98, s24, v14
	v_or_b32_e32 v99, s8, v15
	v_or_b32_e32 v100, s9, v14
	v_add_u32_e32 v10, v3, v1
	v_mad_u64_u32 v[44:45], s[8:9], v0, v25, 0
	v_add_u32_e32 v25, v29, v6
	v_add_u32_e32 v46, v27, v1
	v_add_u32_e32 v68, v90, v6
	v_add_u32_e32 v66, v63, v1
	v_add_u32_e32 v72, v92, v6
	v_add_u32_e32 v70, v91, v1
	v_add_u32_e32 v76, v94, v6
	v_add_u32_e32 v74, v93, v1
	v_add_u32_e32 v80, v96, v6
	v_add_u32_e32 v78, v95, v1
	v_add_u32_e32 v84, v98, v6
	v_add_u32_e32 v82, v97, v1
	v_add_u32_e32 v88, v100, v6
	v_add_u32_e32 v86, v99, v1
	v_mad_u64_u32 v[10:11], s[8:9], v2, v10, 0
	v_lshl_add_u64 v[44:45], v[44:45], 2, v[8:9]
	v_mad_u64_u32 v[46:47], s[8:9], v2, v46, 0
	v_mad_u64_u32 v[64:65], s[8:9], v0, v25, 0
	v_mad_u64_u32 v[66:67], s[8:9], v2, v66, 0
	v_mad_u64_u32 v[68:69], s[8:9], v0, v68, 0
	v_mad_u64_u32 v[70:71], s[8:9], v2, v70, 0
	v_mad_u64_u32 v[72:73], s[8:9], v0, v72, 0
	v_mad_u64_u32 v[74:75], s[8:9], v2, v74, 0
	v_mad_u64_u32 v[76:77], s[8:9], v0, v76, 0
	v_mad_u64_u32 v[78:79], s[8:9], v2, v78, 0
	v_mad_u64_u32 v[80:81], s[8:9], v0, v80, 0
	v_mad_u64_u32 v[82:83], s[8:9], v2, v82, 0
	v_mad_u64_u32 v[84:85], s[8:9], v0, v84, 0
	v_mad_u64_u32 v[86:87], s[8:9], v2, v86, 0
	v_mad_u64_u32 v[88:89], s[8:9], v0, v88, 0
	v_lshl_add_u64 v[10:11], v[10:11], 2, v[8:9]
	v_lshl_add_u64 v[64:65], v[64:65], 2, v[8:9]
	v_lshl_add_u64 v[46:47], v[46:47], 2, v[8:9]
	v_lshl_add_u64 v[68:69], v[68:69], 2, v[8:9]
	v_lshl_add_u64 v[66:67], v[66:67], 2, v[8:9]
	v_lshl_add_u64 v[72:73], v[72:73], 2, v[8:9]
	v_lshl_add_u64 v[70:71], v[70:71], 2, v[8:9]
	v_lshl_add_u64 v[76:77], v[76:77], 2, v[8:9]
	v_lshl_add_u64 v[74:75], v[74:75], 2, v[8:9]
	v_lshl_add_u64 v[80:81], v[80:81], 2, v[8:9]
	v_lshl_add_u64 v[78:79], v[78:79], 2, v[8:9]
	v_lshl_add_u64 v[84:85], v[84:85], 2, v[8:9]
	v_lshl_add_u64 v[82:83], v[82:83], 2, v[8:9]
	v_lshl_add_u64 v[88:89], v[88:89], 2, v[8:9]
	v_lshl_add_u64 v[86:87], v[86:87], 2, v[8:9]
	global_load_dword v25, v[44:45], off nt
	global_load_dword v101, v[10:11], off nt
	global_load_dword v102, v[64:65], off nt
	global_load_dword v103, v[46:47], off nt
	global_load_dword v104, v[68:69], off nt
	global_load_dword v105, v[66:67], off nt
	global_load_dword v106, v[72:73], off nt
	global_load_dword v107, v[70:71], off nt
	global_load_dword v108, v[76:77], off nt
	global_load_dword v109, v[74:75], off nt
	global_load_dword v110, v[80:81], off nt
	global_load_dword v111, v[78:79], off nt
	global_load_dword v112, v[84:85], off nt
	global_load_dword v113, v[82:83], off nt
	global_load_dword v114, v[88:89], off nt
	global_load_dword v115, v[86:87], off nt
	s_add_i32 s6, s6, 16
	s_add_i32 s3, s3, 16
	s_add_i32 s7, s7, -16
	v_mad_u64_u32 v[10:11], s[8:9], v7, s0, v[16:17]
	s_cmp_lg_u32 s7, 0
	v_mad_u64_u32 v[44:45], s[8:9], v3, s0, v[16:17]
	v_mad_u64_u32 v[46:47], s[8:9], v29, s0, v[16:17]
	v_mad_u64_u32 v[64:65], s[8:9], v27, s0, v[16:17]
	v_mad_u64_u32 v[66:67], s[8:9], v90, s0, v[16:17]
	v_mad_u64_u32 v[68:69], s[8:9], v63, s0, v[16:17]
	v_mad_u64_u32 v[70:71], s[8:9], v92, s0, v[16:17]
	v_mad_u64_u32 v[72:73], s[8:9], v91, s0, v[16:17]
	v_mad_u64_u32 v[74:75], s[8:9], v94, s0, v[16:17]
	v_mad_u64_u32 v[76:77], s[8:9], v93, s0, v[16:17]
	v_mad_u64_u32 v[78:79], s[8:9], v96, s0, v[16:17]
	v_mad_u64_u32 v[80:81], s[8:9], v95, s0, v[16:17]
	v_mad_u64_u32 v[82:83], s[8:9], v98, s0, v[16:17]
	v_mad_u64_u32 v[84:85], s[8:9], v97, s0, v[16:17]
	v_mad_u64_u32 v[86:87], s[8:9], v100, s0, v[16:17]
	v_mad_u64_u32 v[88:89], s[8:9], v99, s0, v[16:17]
	s_waitcnt vmcnt(15)
	ds_write_b32 v10, v25
	s_waitcnt vmcnt(14)
	ds_write_b32 v44, v101
	s_waitcnt vmcnt(13)
	ds_write_b32 v46, v102
	s_waitcnt vmcnt(12)
	ds_write_b32 v64, v103
	s_waitcnt vmcnt(11)
	ds_write_b32 v66, v104
	s_waitcnt vmcnt(10)
	ds_write_b32 v68, v105
	s_waitcnt vmcnt(9)
	ds_write_b32 v70, v106
	s_waitcnt vmcnt(8)
	ds_write_b32 v72, v107
	s_waitcnt vmcnt(7)
	ds_write_b32 v74, v108
	s_waitcnt vmcnt(6)
	ds_write_b32 v76, v109
	s_waitcnt vmcnt(5)
	ds_write_b32 v78, v110
	s_waitcnt vmcnt(4)
	ds_write_b32 v80, v111
	s_waitcnt vmcnt(3)
	ds_write_b32 v82, v112
	s_waitcnt vmcnt(2)
	ds_write_b32 v84, v113
	s_waitcnt vmcnt(1)
	ds_write_b32 v86, v114
	s_waitcnt vmcnt(0)
	ds_write_b32 v88, v115
	s_cbranch_scc1 .LBB0_38
	s_waitcnt lgkmcnt(0)
	v_lshl_add_u64 v[0:1], s[56:57], 0, v[4:5]
	v_lshlrev_b32_e32 v2, 1, v6
	ds_read2_b32 v[4:5], v49 offset0:33 offset1:41
	ds_read2_b32 v[6:7], v49 offset1:8
	ds_read2_b32 v[8:9], v49 offset0:66 offset1:74
	ds_read2_b32 v[10:11], v49 offset0:99 offset1:107
	ds_read2_b32 v[44:45], v49 offset0:132 offset1:140
	ds_read2_b32 v[46:47], v49 offset0:165 offset1:173
	ds_read2_b32 v[64:65], v49 offset0:198 offset1:206
	ds_read2_b32 v[66:67], v49 offset0:231 offset1:239
	v_mov_b32_e32 v3, v13
	v_lshl_add_u64 v[0:1], v[0:1], 0, v[2:3]
	v_mov_b32_e32 v27, v13
	v_or_b32_e32 v70, v12, v48
	v_mov_b32_e32 v71, v13
	v_lshl_add_u64 v[68:69], v[0:1], 0, v[26:27]
	v_lshlrev_b64 v[70:71], 11, v[70:71]
	s_waitcnt lgkmcnt(6)
	v_cvt_pk_bf16_f32 v0, v6, v4
	s_waitcnt lgkmcnt(4)
	v_cvt_pk_bf16_f32 v1, v8, v10
	s_waitcnt lgkmcnt(2)
	v_cvt_pk_bf16_f32 v2, v44, v46
	s_waitcnt lgkmcnt(0)
	v_cvt_pk_bf16_f32 v3, v64, v66
	v_lshl_add_u64 v[70:71], v[68:69], 0, v[70:71]
	global_store_dwordx4 v[70:71], v[0:3], off sc1
	v_or_b32_e32 v4, v12, v50
	s_mov_b64 s[6:7], 0
	v_cvt_pk_bf16_f32 v0, v7, v5
	v_cvt_pk_bf16_f32 v1, v9, v11
	v_cvt_pk_bf16_f32 v2, v45, v47
	v_cvt_pk_bf16_f32 v3, v65, v67
	v_mov_b32_e32 v5, v13
	ds_read2_b32 v[6:7], v49 offset0:49 offset1:57
	ds_read2_b32 v[8:9], v49 offset0:16 offset1:24
	ds_read2_b32 v[10:11], v49 offset0:82 offset1:90
	ds_read2_b32 v[44:45], v49 offset0:115 offset1:123
	ds_read2_b32 v[46:47], v49 offset0:148 offset1:156
	ds_read2_b32 v[64:65], v49 offset0:181 offset1:189
	ds_read2_b32 v[66:67], v49 offset0:214 offset1:222
	ds_read2_b32 v[70:71], v49 offset0:247 offset1:255
	v_lshlrev_b64 v[4:5], 11, v[4:5]
	v_lshl_add_u64 v[4:5], v[68:69], 0, v[4:5]
	global_store_dwordx4 v[4:5], v[0:3], off sc1
	v_or_b32_e32 v4, v12, v51
	v_mov_b32_e32 v5, v13
	v_lshlrev_b64 v[4:5], 11, v[4:5]
	s_waitcnt lgkmcnt(6)
	v_cvt_pk_bf16_f32 v0, v8, v6
	s_waitcnt lgkmcnt(4)
	v_cvt_pk_bf16_f32 v1, v10, v44
	s_waitcnt lgkmcnt(2)
	v_cvt_pk_bf16_f32 v2, v46, v64
	s_waitcnt lgkmcnt(0)
	v_cvt_pk_bf16_f32 v3, v66, v70
	v_lshl_add_u64 v[4:5], v[68:69], 0, v[4:5]
	v_or_b32_e32 v12, v12, v52
	global_store_dwordx4 v[4:5], v[0:3], off sc1
	v_lshlrev_b64 v[4:5], 11, v[12:13]
	v_lshl_add_u64 v[4:5], v[68:69], 0, v[4:5]
	v_cvt_pk_bf16_f32 v0, v9, v7
	v_cvt_pk_bf16_f32 v1, v11, v45
	v_cvt_pk_bf16_f32 v2, v47, v65
	v_cvt_pk_bf16_f32 v3, v67, v71
	global_store_dwordx4 v[4:5], v[0:3], off sc1
	s_waitcnt lgkmcnt(0)

.LBB0_344:
	s_lshl_b32 s12, s5, 1
	s_lshl_b32 s13, s4, 1
	v_or_b32_e32 v9, s12, v1
	v_or_b32_e32 v11, s13, v0
	s_add_i32 s14, s12, 4
	s_add_i32 s15, s13, 4
	s_add_i32 s16, s12, 8
	s_add_i32 s17, s13, 8
	s_add_i32 s18, s12, 12
	s_add_i32 s19, s13, 12
	s_add_i32 s20, s12, 16
	s_add_i32 s21, s13, 16
	s_add_i32 s22, s12, 20
	s_add_i32 s23, s13, 20
	s_add_i32 s24, s12, 24
	s_add_i32 s25, s13, 24
	s_add_i32 s12, s12, 28
	s_add_i32 s13, s13, 28
	v_add_u32_e32 v17, v9, v7
	v_add_u32_e32 v43, v11, v16
	v_or_b32_e32 v76, s14, v1
	v_or_b32_e32 v77, s15, v0
	v_or_b32_e32 v78, s16, v1
	v_or_b32_e32 v79, s17, v0
	v_or_b32_e32 v80, s18, v1
	v_or_b32_e32 v81, s19, v0
	v_or_b32_e32 v82, s20, v1
	v_or_b32_e32 v83, s21, v0
	v_or_b32_e32 v84, s22, v1
	v_or_b32_e32 v85, s23, v0
	v_or_b32_e32 v86, s24, v1
	v_or_b32_e32 v87, s25, v0
	v_or_b32_e32 v88, s12, v1
	v_or_b32_e32 v89, s13, v0
	v_ashrrev_i32_e32 v48, 31, v43
	v_ashrrev_i32_e32 v49, 31, v17
	v_mul_lo_u32 v90, v3, v17
	v_mad_u64_u32 v[44:45], s[12:13], v2, v17, 0
	v_mul_lo_u32 v17, v13, v43
	v_mad_u64_u32 v[46:47], s[12:13], v12, v43, 0
	v_add_u32_e32 v43, v76, v7
	v_add_u32_e32 v50, v77, v16
	v_add_u32_e32 v52, v78, v7
	v_add_u32_e32 v54, v79, v16
	v_add_u32_e32 v56, v80, v7
	v_add_u32_e32 v58, v81, v16
	v_add_u32_e32 v60, v82, v7
	v_add_u32_e32 v62, v83, v16
	v_add_u32_e32 v64, v84, v7
	v_add_u32_e32 v66, v85, v16
	v_add_u32_e32 v68, v86, v7
	v_add_u32_e32 v70, v87, v16
	v_add_u32_e32 v72, v88, v7
	v_add_u32_e32 v74, v89, v16
	v_mul_lo_u32 v91, v2, v49
	v_mul_lo_u32 v92, v12, v48
	v_ashrrev_i32_e32 v93, 31, v50
	v_ashrrev_i32_e32 v94, 31, v43
	v_ashrrev_i32_e32 v96, 31, v54
	v_ashrrev_i32_e32 v97, 31, v52
	v_ashrrev_i32_e32 v100, 31, v58
	v_ashrrev_i32_e32 v101, 31, v56
	v_ashrrev_i32_e32 v104, 31, v62
	v_ashrrev_i32_e32 v105, 31, v60
	v_ashrrev_i32_e32 v108, 31, v66
	v_ashrrev_i32_e32 v109, 31, v64
	v_ashrrev_i32_e32 v112, 31, v70
	v_ashrrev_i32_e32 v113, 31, v68
	v_ashrrev_i32_e32 v116, 31, v74
	v_ashrrev_i32_e32 v117, 31, v72
	v_mul_lo_u32 v95, v3, v43
	v_mad_u64_u32 v[48:49], s[12:13], v2, v43, 0
	v_mul_lo_u32 v43, v13, v50
	v_mad_u64_u32 v[50:51], s[12:13], v12, v50, 0
	v_mul_lo_u32 v98, v3, v52
	v_mad_u64_u32 v[52:53], s[12:13], v2, v52, 0
	v_mul_lo_u32 v99, v13, v54
	v_mad_u64_u32 v[54:55], s[12:13], v12, v54, 0
	v_mul_lo_u32 v102, v3, v56
	v_mad_u64_u32 v[56:57], s[12:13], v2, v56, 0
	v_mul_lo_u32 v103, v13, v58
	v_mad_u64_u32 v[58:59], s[12:13], v12, v58, 0
	v_mul_lo_u32 v106, v3, v60
	v_mad_u64_u32 v[60:61], s[12:13], v2, v60, 0
	v_mul_lo_u32 v107, v13, v62
	v_mad_u64_u32 v[62:63], s[12:13], v12, v62, 0
	v_mul_lo_u32 v110, v3, v64
	v_mad_u64_u32 v[64:65], s[12:13], v2, v64, 0
	v_mul_lo_u32 v111, v13, v66
	v_mad_u64_u32 v[66:67], s[12:13], v12, v66, 0
	v_mul_lo_u32 v114, v3, v68
	v_mad_u64_u32 v[68:69], s[12:13], v2, v68, 0
	v_mul_lo_u32 v115, v13, v70
	v_mad_u64_u32 v[70:71], s[12:13], v12, v70, 0
	v_mul_lo_u32 v118, v3, v72
	v_mad_u64_u32 v[72:73], s[12:13], v2, v72, 0
	v_mul_lo_u32 v119, v13, v74
	v_mad_u64_u32 v[74:75], s[12:13], v12, v74, 0
	v_add3_u32 v45, v45, v91, v90
	v_add3_u32 v47, v47, v92, v17
	v_mul_lo_u32 v17, v2, v94
	v_mul_lo_u32 v90, v12, v93
	v_mul_lo_u32 v91, v2, v97
	v_mul_lo_u32 v92, v12, v96
	v_mul_lo_u32 v93, v2, v101
	v_mul_lo_u32 v94, v12, v100
	v_mul_lo_u32 v96, v2, v105
	v_mul_lo_u32 v97, v12, v104
	v_mul_lo_u32 v100, v2, v109
	v_mul_lo_u32 v101, v12, v108
	v_mul_lo_u32 v104, v2, v113
	v_mul_lo_u32 v105, v12, v112
	v_mul_lo_u32 v108, v2, v117
	v_mul_lo_u32 v109, v12, v116
	v_lshl_add_u64 v[46:47], v[46:47], 2, v[18:19]
	v_add3_u32 v49, v49, v17, v95
	v_add3_u32 v51, v51, v90, v43
	v_add3_u32 v53, v53, v91, v98
	v_add3_u32 v55, v55, v92, v99
	v_add3_u32 v57, v57, v93, v102
	v_add3_u32 v59, v59, v94, v103
	v_add3_u32 v61, v61, v96, v106
	v_add3_u32 v63, v63, v97, v107
	v_add3_u32 v65, v65, v100, v110
	v_add3_u32 v67, v67, v101, v111
	v_add3_u32 v69, v69, v104, v114
	v_add3_u32 v71, v71, v105, v115
	v_add3_u32 v73, v73, v108, v118
	v_add3_u32 v75, v75, v109, v119
	v_lshl_add_u64 v[44:45], v[44:45], 2, v[18:19]
	v_lshl_add_u64 v[50:51], v[50:51], 2, v[18:19]
	v_lshl_add_u64 v[48:49], v[48:49], 2, v[18:19]
	v_lshl_add_u64 v[54:55], v[54:55], 2, v[18:19]
	v_lshl_add_u64 v[52:53], v[52:53], 2, v[18:19]
	v_lshl_add_u64 v[58:59], v[58:59], 2, v[18:19]
	v_lshl_add_u64 v[56:57], v[56:57], 2, v[18:19]
	v_lshl_add_u64 v[62:63], v[62:63], 2, v[18:19]
	v_lshl_add_u64 v[60:61], v[60:61], 2, v[18:19]
	v_lshl_add_u64 v[66:67], v[66:67], 2, v[18:19]
	v_lshl_add_u64 v[64:65], v[64:65], 2, v[18:19]
	v_lshl_add_u64 v[70:71], v[70:71], 2, v[18:19]
	v_lshl_add_u64 v[68:69], v[68:69], 2, v[18:19]
	v_lshl_add_u64 v[74:75], v[74:75], 2, v[18:19]
	v_lshl_add_u64 v[72:73], v[72:73], 2, v[18:19]
	global_load_dword v17, v[46:47], off nt
	global_load_dword v43, v[44:45], off nt
	global_load_dword v90, v[50:51], off nt
	global_load_dword v91, v[48:49], off nt
	global_load_dword v92, v[54:55], off nt
	global_load_dword v93, v[52:53], off nt
	global_load_dword v94, v[58:59], off nt
	global_load_dword v95, v[56:57], off nt
	global_load_dword v96, v[62:63], off nt
	global_load_dword v97, v[60:61], off nt
	global_load_dword v98, v[66:67], off nt
	global_load_dword v99, v[64:65], off nt
	global_load_dword v100, v[70:71], off nt
	global_load_dword v101, v[68:69], off nt
	global_load_dword v102, v[74:75], off nt
	global_load_dword v103, v[72:73], off nt
	s_add_i32 s4, s4, 16
	s_add_i32 s5, s5, 16
	s_add_i32 s11, s11, -16
	v_mad_u64_u32 v[44:45], s[12:13], v11, s1, v[6:7]
	s_cmp_lg_u32 s11, 0
	v_mad_u64_u32 v[46:47], s[12:13], v9, s1, v[6:7]
	v_mad_u64_u32 v[48:49], s[12:13], v77, s1, v[6:7]
	v_mad_u64_u32 v[50:51], s[12:13], v76, s1, v[6:7]
	v_mad_u64_u32 v[52:53], s[12:13], v79, s1, v[6:7]
	v_mad_u64_u32 v[54:55], s[12:13], v78, s1, v[6:7]
	v_mad_u64_u32 v[56:57], s[12:13], v81, s1, v[6:7]
	v_mad_u64_u32 v[58:59], s[12:13], v80, s1, v[6:7]
	v_mad_u64_u32 v[60:61], s[12:13], v83, s1, v[6:7]
	v_mad_u64_u32 v[62:63], s[12:13], v82, s1, v[6:7]
	v_mad_u64_u32 v[64:65], s[12:13], v85, s1, v[6:7]
	v_mad_u64_u32 v[66:67], s[12:13], v84, s1, v[6:7]
	v_mad_u64_u32 v[68:69], s[12:13], v87, s1, v[6:7]
	v_mad_u64_u32 v[70:71], s[12:13], v86, s1, v[6:7]
	v_mad_u64_u32 v[72:73], s[12:13], v89, s1, v[6:7]
	v_mad_u64_u32 v[74:75], s[12:13], v88, s1, v[6:7]
	s_waitcnt vmcnt(15)
	ds_write_b32 v44, v17
	s_waitcnt vmcnt(14)
	ds_write_b32 v46, v43
	s_waitcnt vmcnt(13)
	ds_write_b32 v48, v90
	s_waitcnt vmcnt(12)
	ds_write_b32 v50, v91
	s_waitcnt vmcnt(11)
	ds_write_b32 v52, v92
	s_waitcnt vmcnt(10)
	ds_write_b32 v54, v93
	s_waitcnt vmcnt(9)
	ds_write_b32 v56, v94
	s_waitcnt vmcnt(8)
	ds_write_b32 v58, v95
	s_waitcnt vmcnt(7)
	ds_write_b32 v60, v96
	s_waitcnt vmcnt(6)
	ds_write_b32 v62, v97
	s_waitcnt vmcnt(5)
	ds_write_b32 v64, v98
	s_waitcnt vmcnt(4)
	ds_write_b32 v66, v99
	s_waitcnt vmcnt(3)
	ds_write_b32 v68, v100
	s_waitcnt vmcnt(2)
	ds_write_b32 v70, v101
	s_waitcnt vmcnt(1)
	ds_write_b32 v72, v102
	s_waitcnt vmcnt(0)
	ds_write_b32 v74, v103
	s_cbranch_scc1 .LBB0_344
	s_waitcnt lgkmcnt(0)
	v_ashrrev_i32_e32 v17, 31, v16
	v_lshl_add_u64 v[2:3], v[16:17], 1, v[14:15]
	ds_read2_b32 v[16:17], v26 offset0:33 offset1:41
	ds_read2_b32 v[18:19], v26 offset1:8
	ds_read2_b32 v[44:45], v26 offset0:66 offset1:74
	ds_read2_b32 v[46:47], v26 offset0:99 offset1:107
	ds_read2_b32 v[48:49], v26 offset0:132 offset1:140
	ds_read2_b32 v[50:51], v26 offset0:165 offset1:173
	ds_read2_b32 v[52:53], v26 offset0:198 offset1:206
	ds_read2_b32 v[54:55], v26 offset0:231 offset1:239
	v_or_b32_e32 v7, v4, v25
	v_ashrrev_i32_e32 v9, 31, v4
	v_mov_b32_e32 v11, v5
	v_mul_lo_u32 v9, v9, v42
	v_mad_u64_u32 v[56:57], s[4:5], v7, v42, 0
	v_lshl_add_u64 v[2:3], v[2:3], 0, v[10:11]
	v_add_u32_e32 v57, v57, v9
	s_waitcnt lgkmcnt(6)
	v_cvt_pk_bf16_f32 v12, v18, v16
	s_waitcnt lgkmcnt(4)
	v_cvt_pk_bf16_f32 v13, v44, v46
	s_waitcnt lgkmcnt(2)
	v_cvt_pk_bf16_f32 v14, v48, v50
	s_waitcnt lgkmcnt(0)
	v_cvt_pk_bf16_f32 v15, v52, v54
	v_lshl_add_u64 v[56:57], v[56:57], 1, v[2:3]
	global_store_dwordx4 v[56:57], v[12:15], off sc1
	v_or_b32_e32 v7, v4, v27
	s_nop 0
	v_cvt_pk_bf16_f32 v12, v19, v17
	v_cvt_pk_bf16_f32 v13, v45, v47
	v_cvt_pk_bf16_f32 v14, v49, v51
	v_cvt_pk_bf16_f32 v15, v53, v55
	v_mad_u64_u32 v[16:17], s[4:5], v7, v42, 0
	ds_read2_b32 v[18:19], v26 offset0:16 offset1:24
	ds_read2_b32 v[44:45], v26 offset0:49 offset1:57
	ds_read2_b32 v[46:47], v26 offset0:82 offset1:90
	ds_read2_b32 v[48:49], v26 offset0:115 offset1:123
	ds_read2_b32 v[50:51], v26 offset0:148 offset1:156
	ds_read2_b32 v[52:53], v26 offset0:181 offset1:189
	ds_read2_b32 v[54:55], v26 offset0:214 offset1:222
	ds_read2_b32 v[56:57], v26 offset0:247 offset1:255
	v_add_u32_e32 v17, v17, v9
	v_lshl_add_u64 v[16:17], v[16:17], 1, v[2:3]
	v_or_b32_e32 v7, v4, v28
	global_store_dwordx4 v[16:17], v[12:15], off sc1
	v_mad_u64_u32 v[16:17], s[4:5], v7, v42, 0
	v_add_u32_e32 v17, v17, v9
	s_waitcnt lgkmcnt(6)
	v_cvt_pk_bf16_f32 v12, v18, v44
	s_waitcnt lgkmcnt(4)
	v_cvt_pk_bf16_f32 v13, v46, v48
	s_waitcnt lgkmcnt(2)
	v_cvt_pk_bf16_f32 v14, v50, v52
	s_waitcnt lgkmcnt(0)
	v_cvt_pk_bf16_f32 v15, v54, v56
	v_lshl_add_u64 v[16:17], v[16:17], 1, v[2:3]
	v_or_b32_e32 v4, v4, v29
	global_store_dwordx4 v[16:17], v[12:15], off sc1
	v_mad_u64_u32 v[16:17], s[4:5], v4, v42, 0
	v_add_u32_e32 v17, v17, v9
	v_cvt_pk_bf16_f32 v12, v19, v45
	v_cvt_pk_bf16_f32 v13, v47, v49
	v_cvt_pk_bf16_f32 v14, v51, v53
	v_cvt_pk_bf16_f32 v15, v55, v57
	v_lshl_add_u64 v[2:3], v[16:17], 1, v[2:3]
	global_store_dwordx4 v[2:3], v[12:15], off sc1
	s_waitcnt lgkmcnt(0)
	s_branch .LBB0_329

.LBB0_393:
	s_lshl_b32 s9, s5, 1
	s_lshl_b32 s11, s4, 1
	v_or_b32_e32 v9, s9, v1
	v_or_b32_e32 v11, s11, v0
	s_add_i32 s12, s9, 4
	s_add_i32 s13, s11, 4
	s_add_i32 s14, s9, 8
	s_add_i32 s15, s11, 8
	s_add_i32 s16, s9, 12
	s_add_i32 s17, s11, 12
	s_add_i32 s18, s9, 16
	s_add_i32 s19, s11, 16
	s_add_i32 s20, s9, 20
	s_add_i32 s21, s11, 20
	s_add_i32 s22, s9, 24
	s_add_i32 s23, s11, 24
	s_add_i32 s9, s9, 28
	s_add_i32 s11, s11, 28
	v_add_u32_e32 v17, v9, v7
	v_add_u32_e32 v40, v11, v16
	v_or_b32_e32 v70, s12, v1
	v_or_b32_e32 v71, s13, v0
	v_or_b32_e32 v72, s14, v1
	v_or_b32_e32 v73, s15, v0
	v_or_b32_e32 v74, s16, v1
	v_or_b32_e32 v75, s17, v0
	v_or_b32_e32 v76, s18, v1
	v_or_b32_e32 v77, s19, v0
	v_or_b32_e32 v78, s20, v1
	v_or_b32_e32 v79, s21, v0
	v_or_b32_e32 v80, s22, v1
	v_or_b32_e32 v81, s23, v0
	v_or_b32_e32 v82, s9, v1
	v_or_b32_e32 v83, s11, v0
	v_ashrrev_i32_e32 v42, 31, v40
	v_ashrrev_i32_e32 v43, 31, v17
	v_add_u32_e32 v44, v70, v7
	v_add_u32_e32 v45, v71, v16
	v_add_u32_e32 v46, v72, v7
	v_add_u32_e32 v48, v73, v16
	v_add_u32_e32 v50, v74, v7
	v_add_u32_e32 v52, v75, v16
	v_add_u32_e32 v54, v76, v7
	v_add_u32_e32 v56, v77, v16
	v_add_u32_e32 v58, v78, v7
	v_add_u32_e32 v60, v79, v16
	v_add_u32_e32 v62, v80, v7
	v_add_u32_e32 v64, v81, v16
	v_add_u32_e32 v66, v82, v7
	v_add_u32_e32 v68, v83, v16
	v_mul_lo_u32 v84, v3, v17
	v_mad_u64_u32 v[38:39], s[12:13], v2, v17, 0
	v_mul_lo_u32 v17, v13, v40
	v_mad_u64_u32 v[40:41], s[12:13], v12, v40, 0
	v_mul_lo_u32 v85, v2, v43
	v_mul_lo_u32 v86, v12, v42
	v_ashrrev_i32_e32 v87, 31, v45
	v_ashrrev_i32_e32 v88, 31, v44
	v_ashrrev_i32_e32 v91, 31, v48
	v_ashrrev_i32_e32 v92, 31, v46
	v_ashrrev_i32_e32 v95, 31, v52
	v_ashrrev_i32_e32 v96, 31, v50
	v_ashrrev_i32_e32 v99, 31, v56
	v_ashrrev_i32_e32 v100, 31, v54
	v_ashrrev_i32_e32 v103, 31, v60
	v_ashrrev_i32_e32 v104, 31, v58
	v_ashrrev_i32_e32 v107, 31, v64
	v_ashrrev_i32_e32 v108, 31, v62
	v_ashrrev_i32_e32 v111, 31, v68
	v_ashrrev_i32_e32 v112, 31, v66
	v_mul_lo_u32 v89, v3, v44
	v_mad_u64_u32 v[42:43], s[12:13], v2, v44, 0
	v_mul_lo_u32 v90, v13, v45
	v_mad_u64_u32 v[44:45], s[12:13], v12, v45, 0
	v_mul_lo_u32 v93, v3, v46
	v_mad_u64_u32 v[46:47], s[12:13], v2, v46, 0
	v_mul_lo_u32 v94, v13, v48
	v_mad_u64_u32 v[48:49], s[12:13], v12, v48, 0
	v_mul_lo_u32 v97, v3, v50
	v_mad_u64_u32 v[50:51], s[12:13], v2, v50, 0
	v_mul_lo_u32 v98, v13, v52
	v_mad_u64_u32 v[52:53], s[12:13], v12, v52, 0
	v_mul_lo_u32 v101, v3, v54
	v_mad_u64_u32 v[54:55], s[12:13], v2, v54, 0
	v_mul_lo_u32 v102, v13, v56
	v_mad_u64_u32 v[56:57], s[12:13], v12, v56, 0
	v_mul_lo_u32 v105, v3, v58
	v_mad_u64_u32 v[58:59], s[12:13], v2, v58, 0
	v_mul_lo_u32 v106, v13, v60
	v_mad_u64_u32 v[60:61], s[12:13], v12, v60, 0
	v_mul_lo_u32 v109, v3, v62
	v_mad_u64_u32 v[62:63], s[12:13], v2, v62, 0
	v_mul_lo_u32 v110, v13, v64
	v_mad_u64_u32 v[64:65], s[12:13], v12, v64, 0
	v_mul_lo_u32 v113, v3, v66
	v_mad_u64_u32 v[66:67], s[12:13], v2, v66, 0
	v_mul_lo_u32 v114, v13, v68
	v_mad_u64_u32 v[68:69], s[12:13], v12, v68, 0
	v_add3_u32 v39, v39, v85, v84
	v_add3_u32 v41, v41, v86, v17
	v_mul_lo_u32 v17, v2, v88
	v_mul_lo_u32 v84, v12, v87
	v_mul_lo_u32 v85, v2, v92
	v_mul_lo_u32 v86, v12, v91
	v_mul_lo_u32 v87, v2, v96
	v_mul_lo_u32 v88, v12, v95
	v_mul_lo_u32 v91, v2, v100
	v_mul_lo_u32 v92, v12, v99
	v_mul_lo_u32 v95, v2, v104
	v_mul_lo_u32 v96, v12, v103
	v_mul_lo_u32 v99, v2, v108
	v_mul_lo_u32 v100, v12, v107
	v_mul_lo_u32 v103, v2, v112
	v_mul_lo_u32 v104, v12, v111
	v_lshl_add_u64 v[40:41], v[40:41], 2, v[18:19]
	v_add3_u32 v43, v43, v17, v89
	v_add3_u32 v45, v45, v84, v90
	v_add3_u32 v47, v47, v85, v93
	v_add3_u32 v49, v49, v86, v94
	v_add3_u32 v51, v51, v87, v97
	v_add3_u32 v53, v53, v88, v98
	v_add3_u32 v55, v55, v91, v101
	v_add3_u32 v57, v57, v92, v102
	v_add3_u32 v59, v59, v95, v105
	v_add3_u32 v61, v61, v96, v106
	v_add3_u32 v63, v63, v99, v109
	v_add3_u32 v65, v65, v100, v110
	v_add3_u32 v67, v67, v103, v113
	v_add3_u32 v69, v69, v104, v114
	v_lshl_add_u64 v[38:39], v[38:39], 2, v[18:19]
	v_lshl_add_u64 v[44:45], v[44:45], 2, v[18:19]
	v_lshl_add_u64 v[42:43], v[42:43], 2, v[18:19]
	v_lshl_add_u64 v[48:49], v[48:49], 2, v[18:19]
	v_lshl_add_u64 v[46:47], v[46:47], 2, v[18:19]
	v_lshl_add_u64 v[52:53], v[52:53], 2, v[18:19]
	v_lshl_add_u64 v[50:51], v[50:51], 2, v[18:19]
	v_lshl_add_u64 v[56:57], v[56:57], 2, v[18:19]
	v_lshl_add_u64 v[54:55], v[54:55], 2, v[18:19]
	v_lshl_add_u64 v[60:61], v[60:61], 2, v[18:19]
	v_lshl_add_u64 v[58:59], v[58:59], 2, v[18:19]
	v_lshl_add_u64 v[64:65], v[64:65], 2, v[18:19]
	v_lshl_add_u64 v[62:63], v[62:63], 2, v[18:19]
	v_lshl_add_u64 v[68:69], v[68:69], 2, v[18:19]
	v_lshl_add_u64 v[66:67], v[66:67], 2, v[18:19]
	global_load_dword v17, v[40:41], off nt
	global_load_dword v84, v[38:39], off nt
	global_load_dword v85, v[44:45], off nt
	global_load_dword v86, v[42:43], off nt
	global_load_dword v87, v[48:49], off nt
	global_load_dword v88, v[46:47], off nt
	global_load_dword v89, v[52:53], off nt
	global_load_dword v90, v[50:51], off nt
	global_load_dword v91, v[56:57], off nt
	global_load_dword v92, v[54:55], off nt
	global_load_dword v93, v[60:61], off nt
	global_load_dword v94, v[58:59], off nt
	global_load_dword v95, v[64:65], off nt
	global_load_dword v96, v[62:63], off nt
	global_load_dword v97, v[68:69], off nt
	global_load_dword v98, v[66:67], off nt
	s_add_i32 s4, s4, 16
	s_add_i32 s5, s5, 16
	s_add_i32 s8, s8, -16
	v_mad_u64_u32 v[38:39], s[12:13], v11, s1, v[6:7]
	s_cmp_lg_u32 s8, 0
	v_mad_u64_u32 v[40:41], s[12:13], v9, s1, v[6:7]
	v_mad_u64_u32 v[42:43], s[12:13], v71, s1, v[6:7]
	v_mad_u64_u32 v[44:45], s[12:13], v70, s1, v[6:7]
	v_mad_u64_u32 v[46:47], s[12:13], v73, s1, v[6:7]
	v_mad_u64_u32 v[48:49], s[12:13], v72, s1, v[6:7]
	v_mad_u64_u32 v[50:51], s[12:13], v75, s1, v[6:7]
	v_mad_u64_u32 v[52:53], s[12:13], v74, s1, v[6:7]
	v_mad_u64_u32 v[54:55], s[12:13], v77, s1, v[6:7]
	v_mad_u64_u32 v[56:57], s[12:13], v76, s1, v[6:7]
	v_mad_u64_u32 v[58:59], s[12:13], v79, s1, v[6:7]
	v_mad_u64_u32 v[60:61], s[12:13], v78, s1, v[6:7]
	v_mad_u64_u32 v[62:63], s[12:13], v81, s1, v[6:7]
	v_mad_u64_u32 v[64:65], s[12:13], v80, s1, v[6:7]
	v_mad_u64_u32 v[66:67], s[12:13], v83, s1, v[6:7]
	v_mad_u64_u32 v[68:69], s[12:13], v82, s1, v[6:7]
	s_waitcnt vmcnt(15)
	ds_write_b32 v38, v17
	s_waitcnt vmcnt(14)
	ds_write_b32 v40, v84
	s_waitcnt vmcnt(13)
	ds_write_b32 v42, v85
	s_waitcnt vmcnt(12)
	ds_write_b32 v44, v86
	s_waitcnt vmcnt(11)
	ds_write_b32 v46, v87
	s_waitcnt vmcnt(10)
	ds_write_b32 v48, v88
	s_waitcnt vmcnt(9)
	ds_write_b32 v50, v89
	s_waitcnt vmcnt(8)
	ds_write_b32 v52, v90
	s_waitcnt vmcnt(7)
	ds_write_b32 v54, v91
	s_waitcnt vmcnt(6)
	ds_write_b32 v56, v92
	s_waitcnt vmcnt(5)
	ds_write_b32 v58, v93
	s_waitcnt vmcnt(4)
	ds_write_b32 v60, v94
	s_waitcnt vmcnt(3)
	ds_write_b32 v62, v95
	s_waitcnt vmcnt(2)
	ds_write_b32 v64, v96
	s_waitcnt vmcnt(1)
	ds_write_b32 v66, v97
	s_waitcnt vmcnt(0)
	ds_write_b32 v68, v98
	s_cbranch_scc1 .LBB0_393
	s_waitcnt lgkmcnt(0)
	v_ashrrev_i32_e32 v17, 31, v16
	v_lshl_add_u64 v[2:3], v[16:17], 1, v[14:15]
	ds_read2_b32 v[16:17], v21 offset0:33 offset1:41
	ds_read2_b32 v[18:19], v21 offset1:8
	ds_read2_b32 v[38:39], v21 offset0:66 offset1:74
	ds_read2_b32 v[40:41], v21 offset0:99 offset1:107
	ds_read2_b32 v[42:43], v21 offset0:132 offset1:140
	ds_read2_b32 v[44:45], v21 offset0:165 offset1:173
	ds_read2_b32 v[46:47], v21 offset0:198 offset1:206
	ds_read2_b32 v[48:49], v21 offset0:231 offset1:239
	v_or_b32_e32 v7, v4, v20
	v_ashrrev_i32_e32 v9, 31, v4
	v_mov_b32_e32 v11, v5
	v_mul_lo_u32 v9, v9, v37
	v_mad_u64_u32 v[50:51], s[4:5], v7, v37, 0
	v_lshl_add_u64 v[2:3], v[2:3], 0, v[10:11]
	v_add_u32_e32 v51, v51, v9
	s_waitcnt lgkmcnt(6)
	v_cvt_pk_bf16_f32 v12, v18, v16
	s_waitcnt lgkmcnt(4)
	v_cvt_pk_bf16_f32 v13, v38, v40
	s_waitcnt lgkmcnt(2)
	v_cvt_pk_bf16_f32 v14, v42, v44
	s_waitcnt lgkmcnt(0)
	v_cvt_pk_bf16_f32 v15, v46, v48
	v_lshl_add_u64 v[50:51], v[50:51], 1, v[2:3]
	global_store_dwordx4 v[50:51], v[12:15], off sc1
	v_or_b32_e32 v7, v4, v22
	s_nop 0
	v_cvt_pk_bf16_f32 v12, v19, v17
	v_cvt_pk_bf16_f32 v13, v39, v41
	v_cvt_pk_bf16_f32 v14, v43, v45
	v_cvt_pk_bf16_f32 v15, v47, v49
	v_mad_u64_u32 v[16:17], s[4:5], v7, v37, 0
	ds_read2_b32 v[18:19], v21 offset0:16 offset1:24
	ds_read2_b32 v[38:39], v21 offset0:49 offset1:57
	ds_read2_b32 v[40:41], v21 offset0:82 offset1:90
	ds_read2_b32 v[42:43], v21 offset0:115 offset1:123
	ds_read2_b32 v[44:45], v21 offset0:148 offset1:156
	ds_read2_b32 v[46:47], v21 offset0:181 offset1:189
	ds_read2_b32 v[48:49], v21 offset0:214 offset1:222
	ds_read2_b32 v[50:51], v21 offset0:247 offset1:255
	v_add_u32_e32 v17, v17, v9
	v_lshl_add_u64 v[16:17], v[16:17], 1, v[2:3]
	v_or_b32_e32 v7, v4, v23
	global_store_dwordx4 v[16:17], v[12:15], off sc1
	v_mad_u64_u32 v[16:17], s[4:5], v7, v37, 0
	v_add_u32_e32 v17, v17, v9
	s_waitcnt lgkmcnt(6)
	v_cvt_pk_bf16_f32 v12, v18, v38
	s_waitcnt lgkmcnt(4)
	v_cvt_pk_bf16_f32 v13, v40, v42
	s_waitcnt lgkmcnt(2)
	v_cvt_pk_bf16_f32 v14, v44, v46
	s_waitcnt lgkmcnt(0)
	v_cvt_pk_bf16_f32 v15, v48, v50
	v_lshl_add_u64 v[16:17], v[16:17], 1, v[2:3]
	v_or_b32_e32 v4, v4, v24
	global_store_dwordx4 v[16:17], v[12:15], off sc1
	v_mad_u64_u32 v[16:17], s[4:5], v4, v37, 0
	v_add_u32_e32 v17, v17, v9
	v_cvt_pk_bf16_f32 v12, v19, v39
	v_cvt_pk_bf16_f32 v13, v41, v43
	v_cvt_pk_bf16_f32 v14, v45, v47
	v_cvt_pk_bf16_f32 v15, v49, v51
	v_lshl_add_u64 v[2:3], v[16:17], 1, v[2:3]
	global_store_dwordx4 v[2:3], v[12:15], off sc1
	s_waitcnt lgkmcnt(0)
	s_branch .LBB0_378

.Lgu0h_BB0_1032:
	s_lshl_b32 s8, s6, 1
	s_lshl_b32 s9, s5, 1
	v_or_b32_e32 v9, s8, v1
	v_or_b32_e32 v11, s9, v0
	s_add_i32 s10, s8, 4
	s_add_i32 s11, s9, 4
	s_add_i32 s12, s8, 8
	s_add_i32 s13, s9, 8
	s_add_i32 s14, s8, 12
	s_add_i32 s15, s9, 12
	s_add_i32 s16, s8, 16
	s_add_i32 s17, s9, 16
	s_add_i32 s18, s8, 20
	s_add_i32 s19, s9, 20
	s_add_i32 s20, s8, 24
	s_add_i32 s21, s9, 24
	s_add_i32 s8, s8, 28
	s_add_i32 s9, s9, 28
	v_add_u32_e32 v17, v9, v7
	v_add_u32_e32 v37, v11, v16
	v_or_b32_e32 v70, s10, v1
	v_or_b32_e32 v71, s11, v0
	v_or_b32_e32 v72, s12, v1
	v_or_b32_e32 v73, s13, v0
	v_or_b32_e32 v74, s14, v1
	v_or_b32_e32 v75, s15, v0
	v_or_b32_e32 v76, s16, v1
	v_or_b32_e32 v77, s17, v0
	v_or_b32_e32 v78, s18, v1
	v_or_b32_e32 v79, s19, v0
	v_or_b32_e32 v80, s20, v1
	v_or_b32_e32 v81, s21, v0
	v_or_b32_e32 v82, s8, v1
	v_or_b32_e32 v83, s9, v0
	v_ashrrev_i32_e32 v42, 31, v37
	v_ashrrev_i32_e32 v43, 31, v17
	v_mul_lo_u32 v84, v3, v17
	v_mad_u64_u32 v[38:39], s[8:9], v2, v17, 0
	v_mul_lo_u32 v17, v13, v37
	v_mad_u64_u32 v[40:41], s[8:9], v12, v37, 0
	v_add_u32_e32 v37, v70, v7
	v_add_u32_e32 v44, v71, v16
	v_add_u32_e32 v46, v72, v7
	v_add_u32_e32 v48, v73, v16
	v_add_u32_e32 v50, v74, v7
	v_add_u32_e32 v52, v75, v16
	v_add_u32_e32 v54, v76, v7
	v_add_u32_e32 v56, v77, v16
	v_add_u32_e32 v58, v78, v7
	v_add_u32_e32 v60, v79, v16
	v_add_u32_e32 v62, v80, v7
	v_add_u32_e32 v64, v81, v16
	v_add_u32_e32 v66, v82, v7
	v_add_u32_e32 v68, v83, v16
	v_mul_lo_u32 v85, v2, v43
	v_mul_lo_u32 v86, v12, v42
	v_ashrrev_i32_e32 v87, 31, v44
	v_ashrrev_i32_e32 v88, 31, v37
	v_ashrrev_i32_e32 v90, 31, v48
	v_ashrrev_i32_e32 v91, 31, v46
	v_ashrrev_i32_e32 v94, 31, v52
	v_ashrrev_i32_e32 v95, 31, v50
	v_ashrrev_i32_e32 v98, 31, v56
	v_ashrrev_i32_e32 v99, 31, v54
	v_ashrrev_i32_e32 v102, 31, v60
	v_ashrrev_i32_e32 v103, 31, v58
	v_ashrrev_i32_e32 v106, 31, v64
	v_ashrrev_i32_e32 v107, 31, v62
	v_ashrrev_i32_e32 v110, 31, v68
	v_ashrrev_i32_e32 v111, 31, v66
	v_mul_lo_u32 v89, v3, v37
	v_mad_u64_u32 v[42:43], s[8:9], v2, v37, 0
	v_mul_lo_u32 v37, v13, v44
	v_mad_u64_u32 v[44:45], s[8:9], v12, v44, 0
	v_mul_lo_u32 v92, v3, v46
	v_mad_u64_u32 v[46:47], s[8:9], v2, v46, 0
	v_mul_lo_u32 v93, v13, v48
	v_mad_u64_u32 v[48:49], s[8:9], v12, v48, 0
	v_mul_lo_u32 v96, v3, v50
	v_mad_u64_u32 v[50:51], s[8:9], v2, v50, 0
	v_mul_lo_u32 v97, v13, v52
	v_mad_u64_u32 v[52:53], s[8:9], v12, v52, 0
	v_mul_lo_u32 v100, v3, v54
	v_mad_u64_u32 v[54:55], s[8:9], v2, v54, 0
	v_mul_lo_u32 v101, v13, v56
	v_mad_u64_u32 v[56:57], s[8:9], v12, v56, 0
	v_mul_lo_u32 v104, v3, v58
	v_mad_u64_u32 v[58:59], s[8:9], v2, v58, 0
	v_mul_lo_u32 v105, v13, v60
	v_mad_u64_u32 v[60:61], s[8:9], v12, v60, 0
	v_mul_lo_u32 v108, v3, v62
	v_mad_u64_u32 v[62:63], s[8:9], v2, v62, 0
	v_mul_lo_u32 v109, v13, v64
	v_mad_u64_u32 v[64:65], s[8:9], v12, v64, 0
	v_mul_lo_u32 v112, v3, v66
	v_mad_u64_u32 v[66:67], s[8:9], v2, v66, 0
	v_mul_lo_u32 v113, v13, v68
	v_mad_u64_u32 v[68:69], s[8:9], v12, v68, 0
	v_add3_u32 v39, v39, v85, v84
	v_add3_u32 v41, v41, v86, v17
	v_mul_lo_u32 v17, v2, v88
	v_mul_lo_u32 v84, v12, v87
	v_mul_lo_u32 v85, v2, v91
	v_mul_lo_u32 v86, v12, v90
	v_mul_lo_u32 v87, v2, v95
	v_mul_lo_u32 v88, v12, v94
	v_mul_lo_u32 v90, v2, v99
	v_mul_lo_u32 v91, v12, v98
	v_mul_lo_u32 v94, v2, v103
	v_mul_lo_u32 v95, v12, v102
	v_mul_lo_u32 v98, v2, v107
	v_mul_lo_u32 v99, v12, v106
	v_mul_lo_u32 v102, v2, v111
	v_mul_lo_u32 v103, v12, v110
	v_lshl_add_u64 v[40:41], v[40:41], 2, v[18:19]
	v_add3_u32 v43, v43, v17, v89
	v_add3_u32 v45, v45, v84, v37
	v_add3_u32 v47, v47, v85, v92
	v_add3_u32 v49, v49, v86, v93
	v_add3_u32 v51, v51, v87, v96
	v_add3_u32 v53, v53, v88, v97
	v_add3_u32 v55, v55, v90, v100
	v_add3_u32 v57, v57, v91, v101
	v_add3_u32 v59, v59, v94, v104
	v_add3_u32 v61, v61, v95, v105
	v_add3_u32 v63, v63, v98, v108
	v_add3_u32 v65, v65, v99, v109
	v_add3_u32 v67, v67, v102, v112
	v_add3_u32 v69, v69, v103, v113
	v_lshl_add_u64 v[38:39], v[38:39], 2, v[18:19]
	v_lshl_add_u64 v[44:45], v[44:45], 2, v[18:19]
	v_lshl_add_u64 v[42:43], v[42:43], 2, v[18:19]
	v_lshl_add_u64 v[48:49], v[48:49], 2, v[18:19]
	v_lshl_add_u64 v[46:47], v[46:47], 2, v[18:19]
	v_lshl_add_u64 v[52:53], v[52:53], 2, v[18:19]
	v_lshl_add_u64 v[50:51], v[50:51], 2, v[18:19]
	v_lshl_add_u64 v[56:57], v[56:57], 2, v[18:19]
	v_lshl_add_u64 v[54:55], v[54:55], 2, v[18:19]
	v_lshl_add_u64 v[60:61], v[60:61], 2, v[18:19]
	v_lshl_add_u64 v[58:59], v[58:59], 2, v[18:19]
	v_lshl_add_u64 v[64:65], v[64:65], 2, v[18:19]
	v_lshl_add_u64 v[62:63], v[62:63], 2, v[18:19]
	v_lshl_add_u64 v[68:69], v[68:69], 2, v[18:19]
	v_lshl_add_u64 v[66:67], v[66:67], 2, v[18:19]
	global_load_dword v17, v[40:41], off nt
	global_load_dword v37, v[38:39], off nt
	global_load_dword v84, v[44:45], off nt
	global_load_dword v85, v[42:43], off nt
	global_load_dword v86, v[48:49], off nt
	global_load_dword v87, v[46:47], off nt
	global_load_dword v88, v[52:53], off nt
	global_load_dword v89, v[50:51], off nt
	global_load_dword v90, v[56:57], off nt
	global_load_dword v91, v[54:55], off nt
	global_load_dword v92, v[60:61], off nt
	global_load_dword v93, v[58:59], off nt
	global_load_dword v94, v[64:65], off nt
	global_load_dword v95, v[62:63], off nt
	global_load_dword v96, v[68:69], off nt
	global_load_dword v97, v[66:67], off nt
	s_add_i32 s5, s5, 16
	s_add_i32 s6, s6, 16
	s_add_i32 s7, s7, -16
	v_mad_u64_u32 v[38:39], s[8:9], v11, s1, v[6:7]
	s_cmp_lg_u32 s7, 0
	v_mad_u64_u32 v[40:41], s[8:9], v9, s1, v[6:7]
	v_mad_u64_u32 v[42:43], s[8:9], v71, s1, v[6:7]
	v_mad_u64_u32 v[44:45], s[8:9], v70, s1, v[6:7]
	v_mad_u64_u32 v[46:47], s[8:9], v73, s1, v[6:7]
	v_mad_u64_u32 v[48:49], s[8:9], v72, s1, v[6:7]
	v_mad_u64_u32 v[50:51], s[8:9], v75, s1, v[6:7]
	v_mad_u64_u32 v[52:53], s[8:9], v74, s1, v[6:7]
	v_mad_u64_u32 v[54:55], s[8:9], v77, s1, v[6:7]
	v_mad_u64_u32 v[56:57], s[8:9], v76, s1, v[6:7]
	v_mad_u64_u32 v[58:59], s[8:9], v79, s1, v[6:7]
	v_mad_u64_u32 v[60:61], s[8:9], v78, s1, v[6:7]
	v_mad_u64_u32 v[62:63], s[8:9], v81, s1, v[6:7]
	v_mad_u64_u32 v[64:65], s[8:9], v80, s1, v[6:7]
	v_mad_u64_u32 v[66:67], s[8:9], v83, s1, v[6:7]
	v_mad_u64_u32 v[68:69], s[8:9], v82, s1, v[6:7]
	s_waitcnt vmcnt(15)
	ds_write_b32 v38, v17
	s_waitcnt vmcnt(14)
	ds_write_b32 v40, v37
	s_waitcnt vmcnt(13)
	ds_write_b32 v42, v84
	s_waitcnt vmcnt(12)
	ds_write_b32 v44, v85
	s_waitcnt vmcnt(11)
	ds_write_b32 v46, v86
	s_waitcnt vmcnt(10)
	ds_write_b32 v48, v87
	s_waitcnt vmcnt(9)
	ds_write_b32 v50, v88
	s_waitcnt vmcnt(8)
	ds_write_b32 v52, v89
	s_waitcnt vmcnt(7)
	ds_write_b32 v54, v90
	s_waitcnt vmcnt(6)
	ds_write_b32 v56, v91
	s_waitcnt vmcnt(5)
	ds_write_b32 v58, v92
	s_waitcnt vmcnt(4)
	ds_write_b32 v60, v93
	s_waitcnt vmcnt(3)
	ds_write_b32 v62, v94
	s_waitcnt vmcnt(2)
	ds_write_b32 v64, v95
	s_waitcnt vmcnt(1)
	ds_write_b32 v66, v96
	s_waitcnt vmcnt(0)
	ds_write_b32 v68, v97
	s_cbranch_scc1 .Lgu0h_BB0_1032
	s_waitcnt lgkmcnt(0)
	v_ashrrev_i32_e32 v17, 31, v16
	v_lshl_add_u64 v[2:3], v[16:17], 1, v[14:15]
	ds_read2_b32 v[16:17], v20 offset0:33 offset1:41
	ds_read2_b32 v[18:19], v20 offset1:8
	ds_read2_b32 v[38:39], v20 offset0:66 offset1:74
	ds_read2_b32 v[40:41], v20 offset0:99 offset1:107
	ds_read2_b32 v[42:43], v20 offset0:132 offset1:140
	ds_read2_b32 v[44:45], v20 offset0:165 offset1:173
	ds_read2_b32 v[46:47], v20 offset0:198 offset1:206
	ds_read2_b32 v[48:49], v20 offset0:231 offset1:239
	v_or_b32_e32 v7, v4, v185
	v_ashrrev_i32_e32 v9, 31, v4
	v_mov_b32_e32 v11, v5
	v_mul_lo_u32 v9, v9, v36
	v_mad_u64_u32 v[50:51], s[6:7], v7, v36, 0
	v_lshl_add_u64 v[2:3], v[2:3], 0, v[10:11]
	v_add_u32_e32 v51, v51, v9
	s_waitcnt lgkmcnt(6)
	v_cvt_pk_bf16_f32 v12, v18, v16
	s_waitcnt lgkmcnt(4)
	v_cvt_pk_bf16_f32 v13, v38, v40
	s_waitcnt lgkmcnt(2)
	v_cvt_pk_bf16_f32 v14, v42, v44
	s_waitcnt lgkmcnt(0)
	v_cvt_pk_bf16_f32 v15, v46, v48
	v_lshl_add_u64 v[50:51], v[50:51], 1, v[2:3]
	global_store_dwordx4 v[50:51], v[12:15], off sc1
	v_or_b32_e32 v7, v4, v21
	s_add_i32 s5, s0, 0x80
	v_cvt_pk_bf16_f32 v12, v19, v17
	v_cvt_pk_bf16_f32 v13, v39, v41
	v_cvt_pk_bf16_f32 v14, v43, v45
	v_cvt_pk_bf16_f32 v15, v47, v49
	v_mad_u64_u32 v[16:17], s[6:7], v7, v36, 0
	ds_read2_b32 v[18:19], v20 offset0:16 offset1:24
	ds_read2_b32 v[38:39], v20 offset0:49 offset1:57
	ds_read2_b32 v[40:41], v20 offset0:82 offset1:90
	ds_read2_b32 v[42:43], v20 offset0:115 offset1:123
	ds_read2_b32 v[44:45], v20 offset0:148 offset1:156
	ds_read2_b32 v[46:47], v20 offset0:181 offset1:189
	ds_read2_b32 v[48:49], v20 offset0:214 offset1:222
	ds_read2_b32 v[50:51], v20 offset0:247 offset1:255
	v_add_u32_e32 v17, v17, v9
	v_lshl_add_u64 v[16:17], v[16:17], 1, v[2:3]
	v_or_b32_e32 v7, v4, v22
	global_store_dwordx4 v[16:17], v[12:15], off sc1
	v_mad_u64_u32 v[16:17], s[6:7], v7, v36, 0
	v_add_u32_e32 v17, v17, v9
	s_waitcnt lgkmcnt(6)
	v_cvt_pk_bf16_f32 v12, v18, v38
	s_waitcnt lgkmcnt(4)
	v_cvt_pk_bf16_f32 v13, v40, v42
	s_waitcnt lgkmcnt(2)
	v_cvt_pk_bf16_f32 v14, v44, v46
	s_waitcnt lgkmcnt(0)
	v_cvt_pk_bf16_f32 v15, v48, v50
	v_lshl_add_u64 v[16:17], v[16:17], 1, v[2:3]
	v_or_b32_e32 v4, v4, v23
	global_store_dwordx4 v[16:17], v[12:15], off sc1
	v_mad_u64_u32 v[16:17], s[6:7], v4, v36, 0
	v_add_u32_e32 v17, v17, v9
	v_cvt_pk_bf16_f32 v12, v19, v39
	v_cvt_pk_bf16_f32 v13, v41, v43
	v_cvt_pk_bf16_f32 v14, v45, v47
	v_cvt_pk_bf16_f32 v15, v49, v51
	v_lshl_add_u64 v[2:3], v[16:17], 1, v[2:3]
	global_store_dwordx4 v[2:3], v[12:15], off sc1
	s_waitcnt lgkmcnt(0)
	s_cmpk_gt_i32 s0, 0x38f
	s_mov_b32 s0, s5
	s_cbranch_scc0 .Lgu0h_BB0_1019

.LBB0_1032:
	s_lshl_b32 s8, s6, 1
	s_lshl_b32 s9, s5, 1
	v_or_b32_e32 v9, s8, v1
	v_or_b32_e32 v11, s9, v0
	s_add_i32 s10, s8, 4
	s_add_i32 s11, s9, 4
	s_add_i32 s12, s8, 8
	s_add_i32 s13, s9, 8
	s_add_i32 s14, s8, 12
	s_add_i32 s15, s9, 12
	s_add_i32 s16, s8, 16
	s_add_i32 s17, s9, 16
	s_add_i32 s18, s8, 20
	s_add_i32 s19, s9, 20
	s_add_i32 s20, s8, 24
	s_add_i32 s21, s9, 24
	s_add_i32 s8, s8, 28
	s_add_i32 s9, s9, 28
	v_add_u32_e32 v17, v9, v7
	v_add_u32_e32 v37, v11, v16
	v_or_b32_e32 v70, s10, v1
	v_or_b32_e32 v71, s11, v0
	v_or_b32_e32 v72, s12, v1
	v_or_b32_e32 v73, s13, v0
	v_or_b32_e32 v74, s14, v1
	v_or_b32_e32 v75, s15, v0
	v_or_b32_e32 v76, s16, v1
	v_or_b32_e32 v77, s17, v0
	v_or_b32_e32 v78, s18, v1
	v_or_b32_e32 v79, s19, v0
	v_or_b32_e32 v80, s20, v1
	v_or_b32_e32 v81, s21, v0
	v_or_b32_e32 v82, s8, v1
	v_or_b32_e32 v83, s9, v0
	v_ashrrev_i32_e32 v42, 31, v37
	v_ashrrev_i32_e32 v43, 31, v17
	v_mul_lo_u32 v84, v3, v17
	v_mad_u64_u32 v[38:39], s[8:9], v2, v17, 0
	v_mul_lo_u32 v17, v13, v37
	v_mad_u64_u32 v[40:41], s[8:9], v12, v37, 0
	v_add_u32_e32 v37, v70, v7
	v_add_u32_e32 v44, v71, v16
	v_add_u32_e32 v46, v72, v7
	v_add_u32_e32 v48, v73, v16
	v_add_u32_e32 v50, v74, v7
	v_add_u32_e32 v52, v75, v16
	v_add_u32_e32 v54, v76, v7
	v_add_u32_e32 v56, v77, v16
	v_add_u32_e32 v58, v78, v7
	v_add_u32_e32 v60, v79, v16
	v_add_u32_e32 v62, v80, v7
	v_add_u32_e32 v64, v81, v16
	v_add_u32_e32 v66, v82, v7
	v_add_u32_e32 v68, v83, v16
	v_mul_lo_u32 v85, v2, v43
	v_mul_lo_u32 v86, v12, v42
	v_ashrrev_i32_e32 v87, 31, v44
	v_ashrrev_i32_e32 v88, 31, v37
	v_ashrrev_i32_e32 v90, 31, v48
	v_ashrrev_i32_e32 v91, 31, v46
	v_ashrrev_i32_e32 v94, 31, v52
	v_ashrrev_i32_e32 v95, 31, v50
	v_ashrrev_i32_e32 v98, 31, v56
	v_ashrrev_i32_e32 v99, 31, v54
	v_ashrrev_i32_e32 v102, 31, v60
	v_ashrrev_i32_e32 v103, 31, v58
	v_ashrrev_i32_e32 v106, 31, v64
	v_ashrrev_i32_e32 v107, 31, v62
	v_ashrrev_i32_e32 v110, 31, v68
	v_ashrrev_i32_e32 v111, 31, v66
	v_mul_lo_u32 v89, v3, v37
	v_mad_u64_u32 v[42:43], s[8:9], v2, v37, 0
	v_mul_lo_u32 v37, v13, v44
	v_mad_u64_u32 v[44:45], s[8:9], v12, v44, 0
	v_mul_lo_u32 v92, v3, v46
	v_mad_u64_u32 v[46:47], s[8:9], v2, v46, 0
	v_mul_lo_u32 v93, v13, v48
	v_mad_u64_u32 v[48:49], s[8:9], v12, v48, 0
	v_mul_lo_u32 v96, v3, v50
	v_mad_u64_u32 v[50:51], s[8:9], v2, v50, 0
	v_mul_lo_u32 v97, v13, v52
	v_mad_u64_u32 v[52:53], s[8:9], v12, v52, 0
	v_mul_lo_u32 v100, v3, v54
	v_mad_u64_u32 v[54:55], s[8:9], v2, v54, 0
	v_mul_lo_u32 v101, v13, v56
	v_mad_u64_u32 v[56:57], s[8:9], v12, v56, 0
	v_mul_lo_u32 v104, v3, v58
	v_mad_u64_u32 v[58:59], s[8:9], v2, v58, 0
	v_mul_lo_u32 v105, v13, v60
	v_mad_u64_u32 v[60:61], s[8:9], v12, v60, 0
	v_mul_lo_u32 v108, v3, v62
	v_mad_u64_u32 v[62:63], s[8:9], v2, v62, 0
	v_mul_lo_u32 v109, v13, v64
	v_mad_u64_u32 v[64:65], s[8:9], v12, v64, 0
	v_mul_lo_u32 v112, v3, v66
	v_mad_u64_u32 v[66:67], s[8:9], v2, v66, 0
	v_mul_lo_u32 v113, v13, v68
	v_mad_u64_u32 v[68:69], s[8:9], v12, v68, 0
	v_add3_u32 v39, v39, v85, v84
	v_add3_u32 v41, v41, v86, v17
	v_mul_lo_u32 v17, v2, v88
	v_mul_lo_u32 v84, v12, v87
	v_mul_lo_u32 v85, v2, v91
	v_mul_lo_u32 v86, v12, v90
	v_mul_lo_u32 v87, v2, v95
	v_mul_lo_u32 v88, v12, v94
	v_mul_lo_u32 v90, v2, v99
	v_mul_lo_u32 v91, v12, v98
	v_mul_lo_u32 v94, v2, v103
	v_mul_lo_u32 v95, v12, v102
	v_mul_lo_u32 v98, v2, v107
	v_mul_lo_u32 v99, v12, v106
	v_mul_lo_u32 v102, v2, v111
	v_mul_lo_u32 v103, v12, v110
	v_lshl_add_u64 v[40:41], v[40:41], 2, v[18:19]
	v_add3_u32 v43, v43, v17, v89
	v_add3_u32 v45, v45, v84, v37
	v_add3_u32 v47, v47, v85, v92
	v_add3_u32 v49, v49, v86, v93
	v_add3_u32 v51, v51, v87, v96
	v_add3_u32 v53, v53, v88, v97
	v_add3_u32 v55, v55, v90, v100
	v_add3_u32 v57, v57, v91, v101
	v_add3_u32 v59, v59, v94, v104
	v_add3_u32 v61, v61, v95, v105
	v_add3_u32 v63, v63, v98, v108
	v_add3_u32 v65, v65, v99, v109
	v_add3_u32 v67, v67, v102, v112
	v_add3_u32 v69, v69, v103, v113
	v_lshl_add_u64 v[38:39], v[38:39], 2, v[18:19]
	v_lshl_add_u64 v[44:45], v[44:45], 2, v[18:19]
	v_lshl_add_u64 v[42:43], v[42:43], 2, v[18:19]
	v_lshl_add_u64 v[48:49], v[48:49], 2, v[18:19]
	v_lshl_add_u64 v[46:47], v[46:47], 2, v[18:19]
	v_lshl_add_u64 v[52:53], v[52:53], 2, v[18:19]
	v_lshl_add_u64 v[50:51], v[50:51], 2, v[18:19]
	v_lshl_add_u64 v[56:57], v[56:57], 2, v[18:19]
	v_lshl_add_u64 v[54:55], v[54:55], 2, v[18:19]
	v_lshl_add_u64 v[60:61], v[60:61], 2, v[18:19]
	v_lshl_add_u64 v[58:59], v[58:59], 2, v[18:19]
	v_lshl_add_u64 v[64:65], v[64:65], 2, v[18:19]
	v_lshl_add_u64 v[62:63], v[62:63], 2, v[18:19]
	v_lshl_add_u64 v[68:69], v[68:69], 2, v[18:19]
	v_lshl_add_u64 v[66:67], v[66:67], 2, v[18:19]
	global_load_dword v17, v[40:41], off nt
	global_load_dword v37, v[38:39], off nt
	global_load_dword v84, v[44:45], off nt
	global_load_dword v85, v[42:43], off nt
	global_load_dword v86, v[48:49], off nt
	global_load_dword v87, v[46:47], off nt
	global_load_dword v88, v[52:53], off nt
	global_load_dword v89, v[50:51], off nt
	global_load_dword v90, v[56:57], off nt
	global_load_dword v91, v[54:55], off nt
	global_load_dword v92, v[60:61], off nt
	global_load_dword v93, v[58:59], off nt
	global_load_dword v94, v[64:65], off nt
	global_load_dword v95, v[62:63], off nt
	global_load_dword v96, v[68:69], off nt
	global_load_dword v97, v[66:67], off nt
	s_add_i32 s5, s5, 16
	s_add_i32 s6, s6, 16
	s_add_i32 s7, s7, -16
	v_mad_u64_u32 v[38:39], s[8:9], v11, s1, v[6:7]
	s_cmp_lg_u32 s7, 0
	v_mad_u64_u32 v[40:41], s[8:9], v9, s1, v[6:7]
	v_mad_u64_u32 v[42:43], s[8:9], v71, s1, v[6:7]
	v_mad_u64_u32 v[44:45], s[8:9], v70, s1, v[6:7]
	v_mad_u64_u32 v[46:47], s[8:9], v73, s1, v[6:7]
	v_mad_u64_u32 v[48:49], s[8:9], v72, s1, v[6:7]
	v_mad_u64_u32 v[50:51], s[8:9], v75, s1, v[6:7]
	v_mad_u64_u32 v[52:53], s[8:9], v74, s1, v[6:7]
	v_mad_u64_u32 v[54:55], s[8:9], v77, s1, v[6:7]
	v_mad_u64_u32 v[56:57], s[8:9], v76, s1, v[6:7]
	v_mad_u64_u32 v[58:59], s[8:9], v79, s1, v[6:7]
	v_mad_u64_u32 v[60:61], s[8:9], v78, s1, v[6:7]
	v_mad_u64_u32 v[62:63], s[8:9], v81, s1, v[6:7]
	v_mad_u64_u32 v[64:65], s[8:9], v80, s1, v[6:7]
	v_mad_u64_u32 v[66:67], s[8:9], v83, s1, v[6:7]
	v_mad_u64_u32 v[68:69], s[8:9], v82, s1, v[6:7]
	s_waitcnt vmcnt(15)
	ds_write_b32 v38, v17
	s_waitcnt vmcnt(14)
	ds_write_b32 v40, v37
	s_waitcnt vmcnt(13)
	ds_write_b32 v42, v84
	s_waitcnt vmcnt(12)
	ds_write_b32 v44, v85
	s_waitcnt vmcnt(11)
	ds_write_b32 v46, v86
	s_waitcnt vmcnt(10)
	ds_write_b32 v48, v87
	s_waitcnt vmcnt(9)
	ds_write_b32 v50, v88
	s_waitcnt vmcnt(8)
	ds_write_b32 v52, v89
	s_waitcnt vmcnt(7)
	ds_write_b32 v54, v90
	s_waitcnt vmcnt(6)
	ds_write_b32 v56, v91
	s_waitcnt vmcnt(5)
	ds_write_b32 v58, v92
	s_waitcnt vmcnt(4)
	ds_write_b32 v60, v93
	s_waitcnt vmcnt(3)
	ds_write_b32 v62, v94
	s_waitcnt vmcnt(2)
	ds_write_b32 v64, v95
	s_waitcnt vmcnt(1)
	ds_write_b32 v66, v96
	s_waitcnt vmcnt(0)
	ds_write_b32 v68, v97
	s_cbranch_scc1 .LBB0_1032
	s_waitcnt lgkmcnt(0)
	v_ashrrev_i32_e32 v17, 31, v16
	v_lshl_add_u64 v[2:3], v[16:17], 1, v[14:15]
	ds_read2_b32 v[16:17], v20 offset0:33 offset1:41
	ds_read2_b32 v[18:19], v20 offset1:8
	ds_read2_b32 v[38:39], v20 offset0:66 offset1:74
	ds_read2_b32 v[40:41], v20 offset0:99 offset1:107
	ds_read2_b32 v[42:43], v20 offset0:132 offset1:140
	ds_read2_b32 v[44:45], v20 offset0:165 offset1:173
	ds_read2_b32 v[46:47], v20 offset0:198 offset1:206
	ds_read2_b32 v[48:49], v20 offset0:231 offset1:239
	v_or_b32_e32 v7, v4, v185
	v_ashrrev_i32_e32 v9, 31, v4
	v_mov_b32_e32 v11, v5
	v_mul_lo_u32 v9, v9, v36
	v_mad_u64_u32 v[50:51], s[6:7], v7, v36, 0
	v_lshl_add_u64 v[2:3], v[2:3], 0, v[10:11]
	v_add_u32_e32 v51, v51, v9
	s_waitcnt lgkmcnt(6)
	v_cvt_pk_bf16_f32 v12, v18, v16
	s_waitcnt lgkmcnt(4)
	v_cvt_pk_bf16_f32 v13, v38, v40
	s_waitcnt lgkmcnt(2)
	v_cvt_pk_bf16_f32 v14, v42, v44
	s_waitcnt lgkmcnt(0)
	v_cvt_pk_bf16_f32 v15, v46, v48
	v_lshl_add_u64 v[50:51], v[50:51], 1, v[2:3]
	global_store_dwordx4 v[50:51], v[12:15], off sc1
	v_or_b32_e32 v7, v4, v21
	s_add_i32 s5, s0, 0x80
	v_cvt_pk_bf16_f32 v12, v19, v17
	v_cvt_pk_bf16_f32 v13, v39, v41
	v_cvt_pk_bf16_f32 v14, v43, v45
	v_cvt_pk_bf16_f32 v15, v47, v49
	v_mad_u64_u32 v[16:17], s[6:7], v7, v36, 0
	ds_read2_b32 v[18:19], v20 offset0:16 offset1:24
	ds_read2_b32 v[38:39], v20 offset0:49 offset1:57
	ds_read2_b32 v[40:41], v20 offset0:82 offset1:90
	ds_read2_b32 v[42:43], v20 offset0:115 offset1:123
	ds_read2_b32 v[44:45], v20 offset0:148 offset1:156
	ds_read2_b32 v[46:47], v20 offset0:181 offset1:189
	ds_read2_b32 v[48:49], v20 offset0:214 offset1:222
	ds_read2_b32 v[50:51], v20 offset0:247 offset1:255
	v_add_u32_e32 v17, v17, v9
	v_lshl_add_u64 v[16:17], v[16:17], 1, v[2:3]
	v_or_b32_e32 v7, v4, v22
	global_store_dwordx4 v[16:17], v[12:15], off sc1
	v_mad_u64_u32 v[16:17], s[6:7], v7, v36, 0
	v_add_u32_e32 v17, v17, v9
	s_waitcnt lgkmcnt(6)
	v_cvt_pk_bf16_f32 v12, v18, v38
	s_waitcnt lgkmcnt(4)
	v_cvt_pk_bf16_f32 v13, v40, v42
	s_waitcnt lgkmcnt(2)
	v_cvt_pk_bf16_f32 v14, v44, v46
	s_waitcnt lgkmcnt(0)
	v_cvt_pk_bf16_f32 v15, v48, v50
	v_lshl_add_u64 v[16:17], v[16:17], 1, v[2:3]
	v_or_b32_e32 v4, v4, v23
	global_store_dwordx4 v[16:17], v[12:15], off sc1
	v_mad_u64_u32 v[16:17], s[6:7], v4, v36, 0
	v_add_u32_e32 v17, v17, v9
	v_cvt_pk_bf16_f32 v12, v19, v39
	v_cvt_pk_bf16_f32 v13, v41, v43
	v_cvt_pk_bf16_f32 v14, v45, v47
	v_cvt_pk_bf16_f32 v15, v49, v51
	v_lshl_add_u64 v[2:3], v[16:17], 1, v[2:3]
	global_store_dwordx4 v[2:3], v[12:15], off sc1
	s_waitcnt lgkmcnt(0)
	s_cmpk_gt_i32 s0, 0x53f
	s_mov_b32 s0, s5
	s_cbranch_scc0 .LBB0_1019
